# MLA: waves 0-3 publish their tile and meet the barrier right behind the last PV MFMA (max chain and rescale test after it), waves 4-7 behind their 2nd PV MFMA, so MFMAs are in flight across the barrie
# speedup vs baseline: 1.0132x; 1.0123x over previous
; __device__ __forceinline__ void finishSM9(f32x16& p0, f32x16& p1, float alpha, float& l_reg, v8i32& p8) {
; #pragma unroll
;   for (int r = 0; r < 16; ++r) { p0[r] = __builtin_amdgcn_exp2f(p0[r]); p1[r] = __builtin_amdgcn_exp2f(p1[r]); }
;   float ps = 0;
; #pragma unroll
;   for (int r = 0; r < 16; ++r) ps += p0[r];
; #pragma unroll
;   for (int r = 0; r < 16; ++r) ps += p1[r];
;   { auto rr = __builtin_amdgcn_permlane32_swap(__float_as_uint(ps), __float_as_uint(ps), false, false);
;     ps = __uint_as_float(rr[0]) + __uint_as_float(rr[1]); }
;   l_reg = l_reg * alpha + ps;
; #pragma unroll
;   for (int g = 0; g < 4; ++g) {
;     int w = __builtin_amdgcn_cvt_pk_fp8_f32(p0[4 * g], p0[4 * g + 1], 0, false); p8[g] = __builtin_amdgcn_cvt_pk_fp8_f32(p0[4 * g + 2], p0[4 * g + 3], w, true);
;     int u = __builtin_amdgcn_cvt_pk_fp8_f32(p1[4 * g], p1[4 * g + 1], 0, false); p8[4 + g] = __builtin_amdgcn_cvt_pk_fp8_f32(p1[4 * g + 2], p1[4 * g + 3], u, true); }
; }
; __device__ __forceinline__ void pv8(f32x16* o, const char* Vt, const v8i32 p8, int r32, int hi) {
;   const int sw = (r32 >> 2) & 3, a0 = r32 * 64 + (((hi * 2) ^ sw) << 4), a1 = r32 * 64 + (((hi * 2 + 1) ^ sw) << 4);
; #pragma unroll
;   for (int d0 = 0; d0 < 4; ++d0) {
;     const v8i32 vf = cat8(*reinterpret_cast<const v4i32*>(Vt + d0 * 2048 + a0), *reinterpret_cast<const v4i32*>(Vt + d0 * 2048 + a1));
;     o[d0] = __builtin_amdgcn_mfma_scale_f32_32x32x64_f8f6f4(p8, vf, o[d0], 0, 0, 0, 127, 0, 127); }
; }
; __device__ __forceinline__ void qkt9(f32x16& p0, f32x16& p1, const char* Kn, const char* Kr, const v8i32* qf, const float init, int r32, int hi) {
; #pragma unroll
;   for (int r = 0; r < 16; ++r) { p0[r] = init; p1[r] = init; }
; #pragma unroll
;   for (int s = 0; s < 2; ++s) { const int c0 = s * 4 + hi * 2;
;     const v8i32 a0 = cat8(*reinterpret_cast<const v4i32*>(Kn + KN8SW(r32, c0)), *reinterpret_cast<const v4i32*>(Kn + KN8SW(r32, c0 + 1)));
;     const v8i32 a1 = cat8(*reinterpret_cast<const v4i32*>(Kn + 4096 + KN8SW(r32, c0)), *reinterpret_cast<const v4i32*>(Kn + 4096 + KN8SW(r32, c0 + 1)));
;     p0 = __builtin_amdgcn_mfma_scale_f32_32x32x64_f8f6f4(a0, qf[s], p0, 0, 0, 0, 127, 0, 124);
;     p1 = __builtin_amdgcn_mfma_scale_f32_32x32x64_f8f6f4(a1, qf[s], p1, 0, 0, 0, 127, 0, 124); }
;   { const int c0 = hi * 2;
.LBB0_1321:
	global_load_dwordx4 v[158:161], v176, s[18:19]
	global_load_dwordx4 v[162:165], v178, s[16:17]
	global_load_dwordx4 v[154:157], v[180:181], off
	ds_read_b128 v[114:117], v215 offset:24576
	ds_read_b128 v[118:121], v216 offset:24576
	ds_read_b128 v[222:225], v215 offset:28672
	ds_read_b128 v[226:229], v216 offset:28672
	v_add_u32_e32 v176, 0x2000, v176
	v_add_u32_e32 v178, 0x20000, v178
	s_mov_b64 s[20:21], 0x1000
	v_lshl_add_u64 v[180:181], v[180:181], 0, s[20:21]
	v_exp_f32_e32 v0, v82
	v_exp_f32_e32 v177, v83
	v_exp_f32_e32 v179, v84
	v_exp_f32_e32 v254, v85
	v_add_f32_e32 v219, v0, v177
	v_cvt_pk_fp8_f32 v246, v0, v177
	v_add_f32_e32 v219, v179, v219
	v_add_f32_e32 v219, v254, v219
	v_cvt_pk_fp8_f32 v246, v179, v254 op_sel:[0,0,1]
	s_waitcnt lgkmcnt(2)
	v_mfma_scale_f32_32x32x64_f8f6f4 v[114:129], v[114:121], v[146:153], v[230:245], v194, v193 op_sel_hi:[0,0,0]
	v_exp_f32_e32 v0, v86
	v_exp_f32_e32 v177, v87
	v_exp_f32_e32 v179, v88
	v_exp_f32_e32 v254, v89
	v_add_f32_e32 v219, v0, v219
	v_add_f32_e32 v219, v177, v219
	v_cvt_pk_fp8_f32 v247, v0, v177
	v_add_f32_e32 v219, v179, v219
	v_add_f32_e32 v219, v254, v219
	v_cvt_pk_fp8_f32 v247, v179, v254 op_sel:[0,0,1]
	ds_read_b128 v[82:85], v213 offset:24576
	ds_read_b128 v[86:89], v214 offset:24576
	s_waitcnt lgkmcnt(2)
	v_mfma_scale_f32_32x32x64_f8f6f4 v[98:113], v[222:229], v[146:153], v[230:245], v194, v193 op_sel_hi:[0,0,0]
	ds_read_b128 v[222:225], v213 offset:28672
	ds_read_b128 v[226:229], v214 offset:28672
	v_exp_f32_e32 v0, v90
	v_exp_f32_e32 v177, v91
	v_exp_f32_e32 v179, v92
	v_exp_f32_e32 v254, v93
	v_add_f32_e32 v219, v0, v219
	v_add_f32_e32 v219, v177, v219
	v_cvt_pk_fp8_f32 v248, v0, v177
	v_add_f32_e32 v219, v179, v219
	v_add_f32_e32 v219, v254, v219
	v_cvt_pk_fp8_f32 v248, v179, v254 op_sel:[0,0,1]
	v_exp_f32_e32 v0, v94
	v_exp_f32_e32 v177, v95
	v_exp_f32_e32 v179, v96
	v_exp_f32_e32 v254, v97
	v_add_f32_e32 v219, v0, v219
	v_add_f32_e32 v219, v177, v219
	v_cvt_pk_fp8_f32 v249, v0, v177
	v_add_f32_e32 v219, v179, v219
	v_add_f32_e32 v219, v254, v219
	v_cvt_pk_fp8_f32 v249, v179, v254 op_sel:[0,0,1]
	ds_read_b128 v[90:93], v185 offset:36864
	ds_read_b128 v[94:97], v186 offset:36864
	s_waitcnt lgkmcnt(4)
	v_mfma_scale_f32_32x32x64_f8f6f4 v[114:129], v[82:89], v[138:145], v[114:129], v194, v193 op_sel_hi:[0,0,0]
	v_exp_f32_e32 v0, v66
	v_exp_f32_e32 v177, v67
	v_exp_f32_e32 v179, v68
	v_exp_f32_e32 v254, v69
	v_add_f32_e32 v219, v0, v219
	v_add_f32_e32 v219, v177, v219
	v_cvt_pk_fp8_f32 v250, v0, v177
	v_add_f32_e32 v219, v179, v219
	v_add_f32_e32 v219, v254, v219
	v_cvt_pk_fp8_f32 v250, v179, v254 op_sel:[0,0,1]
	s_waitcnt lgkmcnt(2)
	v_mfma_scale_f32_32x32x64_f8f6f4 v[98:113], v[222:229], v[138:145], v[98:113], v194, v193 op_sel_hi:[0,0,0]
	ds_read_b128 v[222:225], v185 offset:38912
	ds_read_b128 v[226:229], v186 offset:38912
	v_exp_f32_e32 v0, v70
	v_exp_f32_e32 v177, v71
	v_exp_f32_e32 v179, v72
	v_exp_f32_e32 v254, v73
	v_add_f32_e32 v219, v0, v219
	v_add_f32_e32 v219, v177, v219
	v_cvt_pk_fp8_f32 v251, v0, v177
	v_add_f32_e32 v219, v179, v219
	v_add_f32_e32 v219, v254, v219
	v_cvt_pk_fp8_f32 v251, v179, v254 op_sel:[0,0,1]
	v_exp_f32_e32 v0, v74
	v_exp_f32_e32 v177, v75
	v_exp_f32_e32 v179, v76
	v_exp_f32_e32 v254, v77
	v_add_f32_e32 v219, v0, v219
	v_add_f32_e32 v219, v177, v219
	v_cvt_pk_fp8_f32 v252, v0, v177
	v_add_f32_e32 v219, v179, v219
	v_add_f32_e32 v219, v254, v219
	v_cvt_pk_fp8_f32 v252, v179, v254 op_sel:[0,0,1]
	s_waitcnt lgkmcnt(2)
	v_mfma_scale_f32_32x32x64_f8f6f4 v[114:129], v[90:97], v[130:137], v[114:129], v194, v193 op_sel_hi:[0,0,0]
	v_exp_f32_e32 v0, v78
	v_exp_f32_e32 v177, v79
	v_exp_f32_e32 v179, v80
	v_exp_f32_e32 v254, v81
	v_add_f32_e32 v219, v0, v219
	v_add_f32_e32 v219, v177, v219
	v_cvt_pk_fp8_f32 v253, v0, v177
	v_add_f32_e32 v219, v179, v219
	v_add_f32_e32 v219, v254, v219
	v_cvt_pk_fp8_f32 v253, v179, v254 op_sel:[0,0,1]
	ds_read_b128 v[90:93], v185 offset:0
	ds_read_b128 v[94:97], v186 offset:0
	ds_read_b128 v[82:85], v185 offset:2048
	ds_read_b128 v[86:89], v186 offset:2048
	ds_read_b128 v[74:77], v185 offset:4096
	ds_read_b128 v[78:81], v186 offset:4096
	ds_read_b128 v[66:69], v185 offset:6144
	ds_read_b128 v[70:73], v186 offset:6144
	s_waitcnt lgkmcnt(8)
	v_mfma_scale_f32_32x32x64_f8f6f4 v[98:113], v[222:229], v[130:137], v[98:113], v194, v193 op_sel_hi:[0,0,0]
	v_mov_b32_e32 v0, v219
	s_nop 1
	v_permlane32_swap_b32_e32 v219, v0
	v_add_f32_e32 v219, v219, v0
	v_fma_f32 v209, v209, v218, v219
	v_max_f32_e32 v177, v114, v115
	v_max3_f32 v177, v177, v116, v117
	v_max3_f32 v177, v177, v118, v119
	v_max3_f32 v177, v177, v120, v121
	v_max3_f32 v177, v177, v122, v123
	v_max3_f32 v177, v177, v124, v125
	v_max3_f32 v177, v177, v126, v127
	v_max3_f32 v177, v177, v128, v129
	s_waitcnt lgkmcnt(6)
	v_mfma_scale_f32_32x32x64_f8f6f4 v[50:65], v[246:253], v[90:97], v[50:65], v194, v194 op_sel_hi:[0,0,0]
	s_waitcnt lgkmcnt(4)
	v_mfma_scale_f32_32x32x64_f8f6f4 v[34:49], v[246:253], v[82:89], v[34:49], v194, v194 op_sel_hi:[0,0,0]
	s_waitcnt lgkmcnt(2)
	v_mfma_scale_f32_32x32x64_f8f6f4 v[18:33], v[246:253], v[74:81], v[18:33], v194, v194 op_sel_hi:[0,0,0]
	s_waitcnt vmcnt(0)
	ds_write_b128 v210, v[158:161] offset:43008
	ds_write_b128 v211, v[162:165] offset:51200
	ds_write_b128 v212, v[154:157] offset:59392
	s_waitcnt lgkmcnt(3)
	v_mfma_scale_f32_32x32x64_f8f6f4 v[2:17], v[246:253], v[66:73], v[2:17], v194, v194 op_sel_hi:[0,0,0]
	s_waitcnt lgkmcnt(0)
	s_barrier
	v_max_f32_e32 v0, v98, v99
	v_max3_f32 v0, v0, v100, v101
	v_max3_f32 v0, v0, v102, v103
	v_max3_f32 v0, v0, v104, v105
	v_max3_f32 v0, v0, v106, v107
	v_max3_f32 v0, v0, v108, v109
	v_max3_f32 v0, v0, v110, v111
	v_max3_f32 v0, v0, v112, v113
	v_max_f32_e32 v177, v177, v0
	v_mov_b32_e32 v0, v177
	v_mov_b32_e32 v221, 1.0
	s_nop 0
	v_permlane32_swap_b32_e32 v177, v0
	v_max_f32_e32 v177, v177, v0
	v_cmp_ge_f32_e32 vcc, s90, v177
	s_cmp_eq_u64 vcc, exec
	s_cbranch_scc0 .Lmla_h0_newmax
; __device__ __forceinline__ void finishSM9(f32x16& p0, f32x16& p1, float alpha, float& l_reg, v8i32& p8) {
; #pragma unroll
;   for (int r = 0; r < 16; ++r) { p0[r] = __builtin_amdgcn_exp2f(p0[r]); p1[r] = __builtin_amdgcn_exp2f(p1[r]); }
;   float ps = 0;
; #pragma unroll
;   for (int r = 0; r < 16; ++r) ps += p0[r];
; #pragma unroll
;   for (int r = 0; r < 16; ++r) ps += p1[r];
;   { auto rr = __builtin_amdgcn_permlane32_swap(__float_as_uint(ps), __float_as_uint(ps), false, false);
;     ps = __uint_as_float(rr[0]) + __uint_as_float(rr[1]); }
;   l_reg = l_reg * alpha + ps;
; #pragma unroll
;   for (int g = 0; g < 4; ++g) {
;     int w = __builtin_amdgcn_cvt_pk_fp8_f32(p0[4 * g], p0[4 * g + 1], 0, false); p8[g] = __builtin_amdgcn_cvt_pk_fp8_f32(p0[4 * g + 2], p0[4 * g + 3], w, true);
;     int u = __builtin_amdgcn_cvt_pk_fp8_f32(p1[4 * g], p1[4 * g + 1], 0, false); p8[4 + g] = __builtin_amdgcn_cvt_pk_fp8_f32(p1[4 * g + 2], p1[4 * g + 3], u, true); }
; }
; __device__ __forceinline__ void pv8(f32x16* o, const char* Vt, const v8i32 p8, int r32, int hi) {
;   const int sw = (r32 >> 2) & 3, a0 = r32 * 64 + (((hi * 2) ^ sw) << 4), a1 = r32 * 64 + (((hi * 2 + 1) ^ sw) << 4);
; #pragma unroll
;   for (int d0 = 0; d0 < 4; ++d0) {
;     const v8i32 vf = cat8(*reinterpret_cast<const v4i32*>(Vt + d0 * 2048 + a0), *reinterpret_cast<const v4i32*>(Vt + d0 * 2048 + a1));
;     o[d0] = __builtin_amdgcn_mfma_scale_f32_32x32x64_f8f6f4(p8, vf, o[d0], 0, 0, 0, 127, 0, 127); }
; }
; __device__ __forceinline__ void qkt9(f32x16& p0, f32x16& p1, const char* Kn, const char* Kr, const v8i32* qf, const float init, int r32, int hi) {
; #pragma unroll
;   for (int r = 0; r < 16; ++r) { p0[r] = init; p1[r] = init; }
; #pragma unroll
;   for (int s = 0; s < 2; ++s) { const int c0 = s * 4 + hi * 2;
;     const v8i32 a0 = cat8(*reinterpret_cast<const v4i32*>(Kn + KN8SW(r32, c0)), *reinterpret_cast<const v4i32*>(Kn + KN8SW(r32, c0 + 1)));
;     const v8i32 a1 = cat8(*reinterpret_cast<const v4i32*>(Kn + 4096 + KN8SW(r32, c0)), *reinterpret_cast<const v4i32*>(Kn + 4096 + KN8SW(r32, c0 + 1)));
;     p0 = __builtin_amdgcn_mfma_scale_f32_32x32x64_f8f6f4(a0, qf[s], p0, 0, 0, 0, 127, 0, 124);
;     p1 = __builtin_amdgcn_mfma_scale_f32_32x32x64_f8f6f4(a1, qf[s], p1, 0, 0, 0, 127, 0, 124); }
;   { const int c0 = hi * 2;
.Lmla_h0_cont:
	global_load_dwordx4 v[158:161], v176, s[18:19]
	global_load_dwordx4 v[162:165], v178, s[16:17]
	global_load_dwordx4 v[154:157], v[180:181], off
	ds_read_b128 v[82:85], v215 offset:51200
	ds_read_b128 v[86:89], v216 offset:51200
	ds_read_b128 v[222:225], v215 offset:55296
	ds_read_b128 v[226:229], v216 offset:55296
	v_add_u32_e32 v176, 0x2000, v176
	v_add_u32_e32 v178, 0x20000, v178
	s_mov_b64 s[20:21], 0x1000
	v_lshl_add_u64 v[180:181], v[180:181], 0, s[20:21]
	v_exp_f32_e32 v0, v114
	v_exp_f32_e32 v177, v115
	v_exp_f32_e32 v179, v116
	v_exp_f32_e32 v254, v117
	v_add_f32_e32 v219, v0, v177
	v_cvt_pk_fp8_f32 v246, v0, v177
	v_add_f32_e32 v219, v179, v219
	v_add_f32_e32 v219, v254, v219
	v_cvt_pk_fp8_f32 v246, v179, v254 op_sel:[0,0,1]
	s_waitcnt lgkmcnt(2)
	v_mfma_scale_f32_32x32x64_f8f6f4 v[82:97], v[82:89], v[146:153], v[230:245], v194, v193 op_sel_hi:[0,0,0]
	v_exp_f32_e32 v0, v118
	v_exp_f32_e32 v177, v119
	v_exp_f32_e32 v179, v120
	v_exp_f32_e32 v254, v121
	v_add_f32_e32 v219, v0, v219
	v_add_f32_e32 v219, v177, v219
	v_cvt_pk_fp8_f32 v247, v0, v177
	v_add_f32_e32 v219, v179, v219
	v_add_f32_e32 v219, v254, v219
	v_cvt_pk_fp8_f32 v247, v179, v254 op_sel:[0,0,1]
	ds_read_b128 v[114:117], v213 offset:51200
	ds_read_b128 v[118:121], v214 offset:51200
	s_waitcnt lgkmcnt(2)
	v_mfma_scale_f32_32x32x64_f8f6f4 v[66:81], v[222:229], v[146:153], v[230:245], v194, v193 op_sel_hi:[0,0,0]
	ds_read_b128 v[222:225], v213 offset:55296
	ds_read_b128 v[226:229], v214 offset:55296
	v_exp_f32_e32 v0, v122
	v_exp_f32_e32 v177, v123
	v_exp_f32_e32 v179, v124
	v_exp_f32_e32 v254, v125
	v_add_f32_e32 v219, v0, v219
	v_add_f32_e32 v219, v177, v219
	v_cvt_pk_fp8_f32 v248, v0, v177
	v_add_f32_e32 v219, v179, v219
	v_add_f32_e32 v219, v254, v219
	v_cvt_pk_fp8_f32 v248, v179, v254 op_sel:[0,0,1]
	v_exp_f32_e32 v0, v126
	v_exp_f32_e32 v177, v127
	v_exp_f32_e32 v179, v128
	v_exp_f32_e32 v254, v129
	v_add_f32_e32 v219, v0, v219
	v_add_f32_e32 v219, v177, v219
	v_cvt_pk_fp8_f32 v249, v0, v177
	v_add_f32_e32 v219, v179, v219
	v_add_f32_e32 v219, v254, v219
	v_cvt_pk_fp8_f32 v249, v179, v254 op_sel:[0,0,1]
	ds_read_b128 v[122:125], v185 offset:59392
	ds_read_b128 v[126:129], v186 offset:59392
	s_waitcnt lgkmcnt(4)
	v_mfma_scale_f32_32x32x64_f8f6f4 v[82:97], v[114:121], v[138:145], v[82:97], v194, v193 op_sel_hi:[0,0,0]
	v_exp_f32_e32 v0, v98
	v_exp_f32_e32 v177, v99
	v_exp_f32_e32 v179, v100
	v_exp_f32_e32 v254, v101
	v_add_f32_e32 v219, v0, v219
	v_add_f32_e32 v219, v177, v219
	v_cvt_pk_fp8_f32 v250, v0, v177
	v_add_f32_e32 v219, v179, v219
	v_add_f32_e32 v219, v254, v219
	v_cvt_pk_fp8_f32 v250, v179, v254 op_sel:[0,0,1]
	s_waitcnt lgkmcnt(2)
	v_mfma_scale_f32_32x32x64_f8f6f4 v[66:81], v[222:229], v[138:145], v[66:81], v194, v193 op_sel_hi:[0,0,0]
	ds_read_b128 v[222:225], v185 offset:61440
	ds_read_b128 v[226:229], v186 offset:61440
	v_exp_f32_e32 v0, v102
	v_exp_f32_e32 v177, v103
	v_exp_f32_e32 v179, v104
	v_exp_f32_e32 v254, v105
	v_add_f32_e32 v219, v0, v219
	v_add_f32_e32 v219, v177, v219
	v_cvt_pk_fp8_f32 v251, v0, v177
	v_add_f32_e32 v219, v179, v219
	v_add_f32_e32 v219, v254, v219
	v_cvt_pk_fp8_f32 v251, v179, v254 op_sel:[0,0,1]
	v_exp_f32_e32 v0, v106
	v_exp_f32_e32 v177, v107
	v_exp_f32_e32 v179, v108
	v_exp_f32_e32 v254, v109
	v_add_f32_e32 v219, v0, v219
	v_add_f32_e32 v219, v177, v219
	v_cvt_pk_fp8_f32 v252, v0, v177
	v_add_f32_e32 v219, v179, v219
	v_add_f32_e32 v219, v254, v219
	v_cvt_pk_fp8_f32 v252, v179, v254 op_sel:[0,0,1]
	s_waitcnt lgkmcnt(2)
	v_mfma_scale_f32_32x32x64_f8f6f4 v[82:97], v[122:129], v[130:137], v[82:97], v194, v193 op_sel_hi:[0,0,0]
	v_exp_f32_e32 v0, v110
	v_exp_f32_e32 v177, v111
	v_exp_f32_e32 v179, v112
	v_exp_f32_e32 v254, v113
	v_add_f32_e32 v219, v0, v219
	v_add_f32_e32 v219, v177, v219
	v_cvt_pk_fp8_f32 v253, v0, v177
	v_add_f32_e32 v219, v179, v219
	v_add_f32_e32 v219, v254, v219
	v_cvt_pk_fp8_f32 v253, v179, v254 op_sel:[0,0,1]
	ds_read_b128 v[122:125], v185 offset:8192
	ds_read_b128 v[126:129], v186 offset:8192
	ds_read_b128 v[114:117], v185 offset:10240
	ds_read_b128 v[118:121], v186 offset:10240
	ds_read_b128 v[106:109], v185 offset:12288
	ds_read_b128 v[110:113], v186 offset:12288
	ds_read_b128 v[98:101], v185 offset:14336
	ds_read_b128 v[102:105], v186 offset:14336
	s_waitcnt lgkmcnt(8)
	v_mfma_scale_f32_32x32x64_f8f6f4 v[66:81], v[222:229], v[130:137], v[66:81], v194, v193 op_sel_hi:[0,0,0]
	v_mov_b32_e32 v0, v219
	s_nop 1
	v_permlane32_swap_b32_e32 v219, v0
	v_add_f32_e32 v219, v219, v0
	v_fma_f32 v209, v209, v221, v219
	v_max_f32_e32 v177, v82, v83
	v_max3_f32 v177, v177, v84, v85
	v_max3_f32 v177, v177, v86, v87
	v_max3_f32 v177, v177, v88, v89
	v_max3_f32 v177, v177, v90, v91
	v_max3_f32 v177, v177, v92, v93
	v_max3_f32 v177, v177, v94, v95
	v_max3_f32 v177, v177, v96, v97
	s_waitcnt lgkmcnt(6)
	v_mfma_scale_f32_32x32x64_f8f6f4 v[50:65], v[246:253], v[122:129], v[50:65], v194, v194 op_sel_hi:[0,0,0]
	s_waitcnt lgkmcnt(4)
	v_mfma_scale_f32_32x32x64_f8f6f4 v[34:49], v[246:253], v[114:121], v[34:49], v194, v194 op_sel_hi:[0,0,0]
	s_waitcnt lgkmcnt(2)
	v_mfma_scale_f32_32x32x64_f8f6f4 v[18:33], v[246:253], v[106:113], v[18:33], v194, v194 op_sel_hi:[0,0,0]
	s_waitcnt vmcnt(0)
	ds_write_b128 v210, v[158:161]
	ds_write_b128 v211, v[162:165] offset:16384
	ds_write_b128 v212, v[154:157] offset:32768
	s_waitcnt lgkmcnt(3)
	v_mfma_scale_f32_32x32x64_f8f6f4 v[2:17], v[246:253], v[98:105], v[2:17], v194, v194 op_sel_hi:[0,0,0]
	s_waitcnt lgkmcnt(0)
	s_barrier
	v_max_f32_e32 v0, v66, v67
	v_max3_f32 v0, v0, v68, v69
	v_max3_f32 v0, v0, v70, v71
	v_max3_f32 v0, v0, v72, v73
	v_max3_f32 v0, v0, v74, v75
	v_max3_f32 v0, v0, v76, v77
	v_max3_f32 v0, v0, v78, v79
	v_max3_f32 v0, v0, v80, v81
	v_max_f32_e32 v177, v177, v0
	v_mov_b32_e32 v0, v177
	v_mov_b32_e32 v218, 1.0
	s_nop 0
	v_permlane32_swap_b32_e32 v177, v0
	v_max_f32_e32 v177, v177, v0
	v_cmp_ge_f32_e32 vcc, s90, v177
	s_cmp_eq_u64 vcc, exec
	s_cbranch_scc0 .Lmla_h1_newmax
; __device__ __forceinline__ void finishSM9(f32x16& p0, f32x16& p1, float alpha, float& l_reg, v8i32& p8) {
; #pragma unroll
;   for (int r = 0; r < 16; ++r) { p0[r] = __builtin_amdgcn_exp2f(p0[r]); p1[r] = __builtin_amdgcn_exp2f(p1[r]); }
;   float ps = 0;
; #pragma unroll
;   for (int r = 0; r < 16; ++r) ps += p0[r];
; #pragma unroll
;   for (int r = 0; r < 16; ++r) ps += p1[r];
;   { auto rr = __builtin_amdgcn_permlane32_swap(__float_as_uint(ps), __float_as_uint(ps), false, false);
;     ps = __uint_as_float(rr[0]) + __uint_as_float(rr[1]); }
;   l_reg = l_reg * alpha + ps;
; #pragma unroll
;   for (int g = 0; g < 4; ++g) {
;     int w = __builtin_amdgcn_cvt_pk_fp8_f32(p0[4 * g], p0[4 * g + 1], 0, false); p8[g] = __builtin_amdgcn_cvt_pk_fp8_f32(p0[4 * g + 2], p0[4 * g + 3], w, true);
;     int u = __builtin_amdgcn_cvt_pk_fp8_f32(p1[4 * g], p1[4 * g + 1], 0, false); p8[4 + g] = __builtin_amdgcn_cvt_pk_fp8_f32(p1[4 * g + 2], p1[4 * g + 3], u, true); }
; }
; __device__ __forceinline__ void pv8(f32x16* o, const char* Vt, const v8i32 p8, int r32, int hi) {
;   const int sw = (r32 >> 2) & 3, a0 = r32 * 64 + (((hi * 2) ^ sw) << 4), a1 = r32 * 64 + (((hi * 2 + 1) ^ sw) << 4);
; #pragma unroll
;   for (int d0 = 0; d0 < 4; ++d0) {
;     const v8i32 vf = cat8(*reinterpret_cast<const v4i32*>(Vt + d0 * 2048 + a0), *reinterpret_cast<const v4i32*>(Vt + d0 * 2048 + a1));
;     o[d0] = __builtin_amdgcn_mfma_scale_f32_32x32x64_f8f6f4(p8, vf, o[d0], 0, 0, 0, 127, 0, 127); }
; }
; __device__ __forceinline__ void qkt9(f32x16& p0, f32x16& p1, const char* Kn, const char* Kr, const v8i32* qf, const float init, int r32, int hi) {
; #pragma unroll
;   for (int r = 0; r < 16; ++r) { p0[r] = init; p1[r] = init; }
; #pragma unroll
;   for (int s = 0; s < 2; ++s) { const int c0 = s * 4 + hi * 2;
;     const v8i32 a0 = cat8(*reinterpret_cast<const v4i32*>(Kn + KN8SW(r32, c0)), *reinterpret_cast<const v4i32*>(Kn + KN8SW(r32, c0 + 1)));
;     const v8i32 a1 = cat8(*reinterpret_cast<const v4i32*>(Kn + 4096 + KN8SW(r32, c0)), *reinterpret_cast<const v4i32*>(Kn + 4096 + KN8SW(r32, c0 + 1)));
;     p0 = __builtin_amdgcn_mfma_scale_f32_32x32x64_f8f6f4(a0, qf[s], p0, 0, 0, 0, 127, 0, 124);
;     p1 = __builtin_amdgcn_mfma_scale_f32_32x32x64_f8f6f4(a1, qf[s], p1, 0, 0, 0, 127, 0, 124); }
;   { const int c0 = hi * 2;
.Lmla_h1_cont:
	global_load_dwordx4 v[158:161], v176, s[18:19]
	global_load_dwordx4 v[162:165], v178, s[16:17]
	global_load_dwordx4 v[154:157], v[180:181], off
	ds_read_b128 v[114:117], v215 offset:16384
	ds_read_b128 v[118:121], v216 offset:16384
	ds_read_b128 v[222:225], v215 offset:20480
	ds_read_b128 v[226:229], v216 offset:20480
	v_add_u32_e32 v176, 0x2000, v176
	v_add_u32_e32 v178, 0x20000, v178
	s_mov_b64 s[20:21], 0x1000
	v_lshl_add_u64 v[180:181], v[180:181], 0, s[20:21]
	v_exp_f32_e32 v0, v82
	v_exp_f32_e32 v177, v83
	v_exp_f32_e32 v179, v84
	v_exp_f32_e32 v254, v85
	v_add_f32_e32 v219, v0, v177
	v_cvt_pk_fp8_f32 v246, v0, v177
	v_add_f32_e32 v219, v179, v219
	v_add_f32_e32 v219, v254, v219
	v_cvt_pk_fp8_f32 v246, v179, v254 op_sel:[0,0,1]
	s_waitcnt lgkmcnt(2)
	v_mfma_scale_f32_32x32x64_f8f6f4 v[114:129], v[114:121], v[146:153], v[230:245], v194, v193 op_sel_hi:[0,0,0]
	v_exp_f32_e32 v0, v86
	v_exp_f32_e32 v177, v87
	v_exp_f32_e32 v179, v88
	v_exp_f32_e32 v254, v89
	v_add_f32_e32 v219, v0, v219
	v_add_f32_e32 v219, v177, v219
	v_cvt_pk_fp8_f32 v247, v0, v177
	v_add_f32_e32 v219, v179, v219
	v_add_f32_e32 v219, v254, v219
	v_cvt_pk_fp8_f32 v247, v179, v254 op_sel:[0,0,1]
	ds_read_b128 v[82:85], v213 offset:16384
	ds_read_b128 v[86:89], v214 offset:16384
	s_waitcnt lgkmcnt(2)
	v_mfma_scale_f32_32x32x64_f8f6f4 v[98:113], v[222:229], v[146:153], v[230:245], v194, v193 op_sel_hi:[0,0,0]
	ds_read_b128 v[222:225], v213 offset:20480
	ds_read_b128 v[226:229], v214 offset:20480
	v_exp_f32_e32 v0, v90
	v_exp_f32_e32 v177, v91
	v_exp_f32_e32 v179, v92
	v_exp_f32_e32 v254, v93
	v_add_f32_e32 v219, v0, v219
	v_add_f32_e32 v219, v177, v219
	v_cvt_pk_fp8_f32 v248, v0, v177
	v_add_f32_e32 v219, v179, v219
	v_add_f32_e32 v219, v254, v219
	v_cvt_pk_fp8_f32 v248, v179, v254 op_sel:[0,0,1]
	v_exp_f32_e32 v0, v94
	v_exp_f32_e32 v177, v95
	v_exp_f32_e32 v179, v96
	v_exp_f32_e32 v254, v97
	v_add_f32_e32 v219, v0, v219
	v_add_f32_e32 v219, v177, v219
	v_cvt_pk_fp8_f32 v249, v0, v177
	v_add_f32_e32 v219, v179, v219
	v_add_f32_e32 v219, v254, v219
	v_cvt_pk_fp8_f32 v249, v179, v254 op_sel:[0,0,1]
	ds_read_b128 v[90:93], v185 offset:32768
	ds_read_b128 v[94:97], v186 offset:32768
	s_waitcnt lgkmcnt(4)
	v_mfma_scale_f32_32x32x64_f8f6f4 v[114:129], v[82:89], v[138:145], v[114:129], v194, v193 op_sel_hi:[0,0,0]
	v_exp_f32_e32 v0, v66
	v_exp_f32_e32 v177, v67
	v_exp_f32_e32 v179, v68
	v_exp_f32_e32 v254, v69
	v_add_f32_e32 v219, v0, v219
	v_add_f32_e32 v219, v177, v219
	v_cvt_pk_fp8_f32 v250, v0, v177
	v_add_f32_e32 v219, v179, v219
	v_add_f32_e32 v219, v254, v219
	v_cvt_pk_fp8_f32 v250, v179, v254 op_sel:[0,0,1]
	s_waitcnt lgkmcnt(2)
	v_mfma_scale_f32_32x32x64_f8f6f4 v[98:113], v[222:229], v[138:145], v[98:113], v194, v193 op_sel_hi:[0,0,0]
	ds_read_b128 v[222:225], v185 offset:34816
	ds_read_b128 v[226:229], v186 offset:34816
	v_exp_f32_e32 v0, v70
	v_exp_f32_e32 v177, v71
	v_exp_f32_e32 v179, v72
	v_exp_f32_e32 v254, v73
	v_add_f32_e32 v219, v0, v219
	v_add_f32_e32 v219, v177, v219
	v_cvt_pk_fp8_f32 v251, v0, v177
	v_add_f32_e32 v219, v179, v219
	v_add_f32_e32 v219, v254, v219
	v_cvt_pk_fp8_f32 v251, v179, v254 op_sel:[0,0,1]
	v_exp_f32_e32 v0, v74
	v_exp_f32_e32 v177, v75
	v_exp_f32_e32 v179, v76
	v_exp_f32_e32 v254, v77
	v_add_f32_e32 v219, v0, v219
	v_add_f32_e32 v219, v177, v219
	v_cvt_pk_fp8_f32 v252, v0, v177
	v_add_f32_e32 v219, v179, v219
	v_add_f32_e32 v219, v254, v219
	v_cvt_pk_fp8_f32 v252, v179, v254 op_sel:[0,0,1]
	s_waitcnt lgkmcnt(2)
	v_mfma_scale_f32_32x32x64_f8f6f4 v[114:129], v[90:97], v[130:137], v[114:129], v194, v193 op_sel_hi:[0,0,0]
	v_exp_f32_e32 v0, v78
	v_exp_f32_e32 v177, v79
	v_exp_f32_e32 v179, v80
	v_exp_f32_e32 v254, v81
	v_add_f32_e32 v219, v0, v219
	v_add_f32_e32 v219, v177, v219
	v_cvt_pk_fp8_f32 v253, v0, v177
	v_add_f32_e32 v219, v179, v219
	v_add_f32_e32 v219, v254, v219
	v_cvt_pk_fp8_f32 v253, v179, v254 op_sel:[0,0,1]
	ds_read_b128 v[90:93], v185 offset:43008
	ds_read_b128 v[94:97], v186 offset:43008
	ds_read_b128 v[82:85], v185 offset:45056
	ds_read_b128 v[86:89], v186 offset:45056
	ds_read_b128 v[74:77], v185 offset:47104
	ds_read_b128 v[78:81], v186 offset:47104
	ds_read_b128 v[66:69], v185 offset:49152
	ds_read_b128 v[70:73], v186 offset:49152
	s_waitcnt lgkmcnt(8)
	v_mfma_scale_f32_32x32x64_f8f6f4 v[98:113], v[222:229], v[130:137], v[98:113], v194, v193 op_sel_hi:[0,0,0]
	v_mov_b32_e32 v0, v219
	s_nop 1
	v_permlane32_swap_b32_e32 v219, v0
	v_add_f32_e32 v219, v219, v0
	v_fma_f32 v209, v209, v218, v219
	v_max_f32_e32 v177, v114, v115
	v_max3_f32 v177, v177, v116, v117
	v_max3_f32 v177, v177, v118, v119
	v_max3_f32 v177, v177, v120, v121
	v_max3_f32 v177, v177, v122, v123
	v_max3_f32 v177, v177, v124, v125
	v_max3_f32 v177, v177, v126, v127
	v_max3_f32 v177, v177, v128, v129
	s_waitcnt lgkmcnt(6)
	v_mfma_scale_f32_32x32x64_f8f6f4 v[50:65], v[246:253], v[90:97], v[50:65], v194, v194 op_sel_hi:[0,0,0]
	s_waitcnt lgkmcnt(4)
	v_mfma_scale_f32_32x32x64_f8f6f4 v[34:49], v[246:253], v[82:89], v[34:49], v194, v194 op_sel_hi:[0,0,0]
	s_waitcnt lgkmcnt(2)
	v_mfma_scale_f32_32x32x64_f8f6f4 v[18:33], v[246:253], v[74:81], v[18:33], v194, v194 op_sel_hi:[0,0,0]
	s_waitcnt vmcnt(0)
	ds_write_b128 v210, v[158:161] offset:8192
	ds_write_b128 v211, v[162:165] offset:24576
	ds_write_b128 v212, v[154:157] offset:36864
	s_waitcnt lgkmcnt(3)
	v_mfma_scale_f32_32x32x64_f8f6f4 v[2:17], v[246:253], v[66:73], v[2:17], v194, v194 op_sel_hi:[0,0,0]
	s_waitcnt lgkmcnt(0)
	s_barrier
	v_max_f32_e32 v0, v98, v99
	v_max3_f32 v0, v0, v100, v101
	v_max3_f32 v0, v0, v102, v103
	v_max3_f32 v0, v0, v104, v105
	v_max3_f32 v0, v0, v106, v107
	v_max3_f32 v0, v0, v108, v109
	v_max3_f32 v0, v0, v110, v111
	v_max3_f32 v0, v0, v112, v113
	v_max_f32_e32 v177, v177, v0
	v_mov_b32_e32 v0, v177
	v_mov_b32_e32 v221, 1.0
	s_nop 0
	v_permlane32_swap_b32_e32 v177, v0
	v_max_f32_e32 v177, v177, v0
	v_cmp_ge_f32_e32 vcc, s90, v177
	s_cmp_eq_u64 vcc, exec
	s_cbranch_scc0 .Lmla_h2_newmax
; __device__ __forceinline__ void finishSM9(f32x16& p0, f32x16& p1, float alpha, float& l_reg, v8i32& p8) {
; #pragma unroll
;   for (int r = 0; r < 16; ++r) { p0[r] = __builtin_amdgcn_exp2f(p0[r]); p1[r] = __builtin_amdgcn_exp2f(p1[r]); }
;   float ps = 0;
; #pragma unroll
;   for (int r = 0; r < 16; ++r) ps += p0[r];
; #pragma unroll
;   for (int r = 0; r < 16; ++r) ps += p1[r];
;   { auto rr = __builtin_amdgcn_permlane32_swap(__float_as_uint(ps), __float_as_uint(ps), false, false);
;     ps = __uint_as_float(rr[0]) + __uint_as_float(rr[1]); }
;   l_reg = l_reg * alpha + ps;
; #pragma unroll
;   for (int g = 0; g < 4; ++g) {
;     int w = __builtin_amdgcn_cvt_pk_fp8_f32(p0[4 * g], p0[4 * g + 1], 0, false); p8[g] = __builtin_amdgcn_cvt_pk_fp8_f32(p0[4 * g + 2], p0[4 * g + 3], w, true);
;     int u = __builtin_amdgcn_cvt_pk_fp8_f32(p1[4 * g], p1[4 * g + 1], 0, false); p8[4 + g] = __builtin_amdgcn_cvt_pk_fp8_f32(p1[4 * g + 2], p1[4 * g + 3], u, true); }
; }
; __device__ __forceinline__ void pv8(f32x16* o, const char* Vt, const v8i32 p8, int r32, int hi) {
;   const int sw = (r32 >> 2) & 3, a0 = r32 * 64 + (((hi * 2) ^ sw) << 4), a1 = r32 * 64 + (((hi * 2 + 1) ^ sw) << 4);
; #pragma unroll
;   for (int d0 = 0; d0 < 4; ++d0) {
;     const v8i32 vf = cat8(*reinterpret_cast<const v4i32*>(Vt + d0 * 2048 + a0), *reinterpret_cast<const v4i32*>(Vt + d0 * 2048 + a1));
;     o[d0] = __builtin_amdgcn_mfma_scale_f32_32x32x64_f8f6f4(p8, vf, o[d0], 0, 0, 0, 127, 0, 127); }
; }
; __device__ __forceinline__ void qkt9(f32x16& p0, f32x16& p1, const char* Kn, const char* Kr, const v8i32* qf, const float init, int r32, int hi) {
; #pragma unroll
;   for (int r = 0; r < 16; ++r) { p0[r] = init; p1[r] = init; }
; #pragma unroll
;   for (int s = 0; s < 2; ++s) { const int c0 = s * 4 + hi * 2;
;     const v8i32 a0 = cat8(*reinterpret_cast<const v4i32*>(Kn + KN8SW(r32, c0)), *reinterpret_cast<const v4i32*>(Kn + KN8SW(r32, c0 + 1)));
;     const v8i32 a1 = cat8(*reinterpret_cast<const v4i32*>(Kn + 4096 + KN8SW(r32, c0)), *reinterpret_cast<const v4i32*>(Kn + 4096 + KN8SW(r32, c0 + 1)));
;     p0 = __builtin_amdgcn_mfma_scale_f32_32x32x64_f8f6f4(a0, qf[s], p0, 0, 0, 0, 127, 0, 124);
;     p1 = __builtin_amdgcn_mfma_scale_f32_32x32x64_f8f6f4(a1, qf[s], p1, 0, 0, 0, 127, 0, 124); }
;   { const int c0 = hi * 2;
.Lmla_h2_cont:
	global_load_dwordx4 v[158:161], v176, s[18:19]
	global_load_dwordx4 v[162:165], v178, s[16:17]
	global_load_dwordx4 v[154:157], v[180:181], off
	ds_read_b128 v[82:85], v215 offset:24576
	ds_read_b128 v[86:89], v216 offset:24576
	ds_read_b128 v[222:225], v215 offset:28672
	ds_read_b128 v[226:229], v216 offset:28672
	v_add_u32_e32 v176, 0x2000, v176
	v_add_u32_e32 v178, 0x20000, v178
	s_mov_b64 s[20:21], 0x1000
	v_lshl_add_u64 v[180:181], v[180:181], 0, s[20:21]
	v_exp_f32_e32 v0, v114
	v_exp_f32_e32 v177, v115
	v_exp_f32_e32 v179, v116
	v_exp_f32_e32 v254, v117
	v_add_f32_e32 v219, v0, v177
	v_cvt_pk_fp8_f32 v246, v0, v177
	v_add_f32_e32 v219, v179, v219
	v_add_f32_e32 v219, v254, v219
	v_cvt_pk_fp8_f32 v246, v179, v254 op_sel:[0,0,1]
	s_waitcnt lgkmcnt(2)
	v_mfma_scale_f32_32x32x64_f8f6f4 v[82:97], v[82:89], v[146:153], v[230:245], v194, v193 op_sel_hi:[0,0,0]
	v_exp_f32_e32 v0, v118
	v_exp_f32_e32 v177, v119
	v_exp_f32_e32 v179, v120
	v_exp_f32_e32 v254, v121
	v_add_f32_e32 v219, v0, v219
	v_add_f32_e32 v219, v177, v219
	v_cvt_pk_fp8_f32 v247, v0, v177
	v_add_f32_e32 v219, v179, v219
	v_add_f32_e32 v219, v254, v219
	v_cvt_pk_fp8_f32 v247, v179, v254 op_sel:[0,0,1]
	ds_read_b128 v[114:117], v213 offset:24576
	ds_read_b128 v[118:121], v214 offset:24576
	s_waitcnt lgkmcnt(2)
	v_mfma_scale_f32_32x32x64_f8f6f4 v[66:81], v[222:229], v[146:153], v[230:245], v194, v193 op_sel_hi:[0,0,0]
	ds_read_b128 v[222:225], v213 offset:28672
	ds_read_b128 v[226:229], v214 offset:28672
	v_exp_f32_e32 v0, v122
	v_exp_f32_e32 v177, v123
	v_exp_f32_e32 v179, v124
	v_exp_f32_e32 v254, v125
	v_add_f32_e32 v219, v0, v219
	v_add_f32_e32 v219, v177, v219
	v_cvt_pk_fp8_f32 v248, v0, v177
	v_add_f32_e32 v219, v179, v219
	v_add_f32_e32 v219, v254, v219
	v_cvt_pk_fp8_f32 v248, v179, v254 op_sel:[0,0,1]
	v_exp_f32_e32 v0, v126
	v_exp_f32_e32 v177, v127
	v_exp_f32_e32 v179, v128
	v_exp_f32_e32 v254, v129
	v_add_f32_e32 v219, v0, v219
	v_add_f32_e32 v219, v177, v219
	v_cvt_pk_fp8_f32 v249, v0, v177
	v_add_f32_e32 v219, v179, v219
	v_add_f32_e32 v219, v254, v219
	v_cvt_pk_fp8_f32 v249, v179, v254 op_sel:[0,0,1]
	ds_read_b128 v[122:125], v185 offset:36864
	ds_read_b128 v[126:129], v186 offset:36864
	s_waitcnt lgkmcnt(4)
	v_mfma_scale_f32_32x32x64_f8f6f4 v[82:97], v[114:121], v[138:145], v[82:97], v194, v193 op_sel_hi:[0,0,0]
	v_exp_f32_e32 v0, v98
	v_exp_f32_e32 v177, v99
	v_exp_f32_e32 v179, v100
	v_exp_f32_e32 v254, v101
	v_add_f32_e32 v219, v0, v219
	v_add_f32_e32 v219, v177, v219
	v_cvt_pk_fp8_f32 v250, v0, v177
	v_add_f32_e32 v219, v179, v219
	v_add_f32_e32 v219, v254, v219
	v_cvt_pk_fp8_f32 v250, v179, v254 op_sel:[0,0,1]
	s_waitcnt lgkmcnt(2)
	v_mfma_scale_f32_32x32x64_f8f6f4 v[66:81], v[222:229], v[138:145], v[66:81], v194, v193 op_sel_hi:[0,0,0]
	ds_read_b128 v[222:225], v185 offset:38912
	ds_read_b128 v[226:229], v186 offset:38912
	v_exp_f32_e32 v0, v102
	v_exp_f32_e32 v177, v103
	v_exp_f32_e32 v179, v104
	v_exp_f32_e32 v254, v105
	v_add_f32_e32 v219, v0, v219
	v_add_f32_e32 v219, v177, v219
	v_cvt_pk_fp8_f32 v251, v0, v177
	v_add_f32_e32 v219, v179, v219
	v_add_f32_e32 v219, v254, v219
	v_cvt_pk_fp8_f32 v251, v179, v254 op_sel:[0,0,1]
	v_exp_f32_e32 v0, v106
	v_exp_f32_e32 v177, v107
	v_exp_f32_e32 v179, v108
	v_exp_f32_e32 v254, v109
	v_add_f32_e32 v219, v0, v219
	v_add_f32_e32 v219, v177, v219
	v_cvt_pk_fp8_f32 v252, v0, v177
	v_add_f32_e32 v219, v179, v219
	v_add_f32_e32 v219, v254, v219
	v_cvt_pk_fp8_f32 v252, v179, v254 op_sel:[0,0,1]
	s_waitcnt lgkmcnt(2)
	v_mfma_scale_f32_32x32x64_f8f6f4 v[82:97], v[122:129], v[130:137], v[82:97], v194, v193 op_sel_hi:[0,0,0]
	v_exp_f32_e32 v0, v110
	v_exp_f32_e32 v177, v111
	v_exp_f32_e32 v179, v112
	v_exp_f32_e32 v254, v113
	v_add_f32_e32 v219, v0, v219
	v_add_f32_e32 v219, v177, v219
	v_cvt_pk_fp8_f32 v253, v0, v177
	v_add_f32_e32 v219, v179, v219
	v_add_f32_e32 v219, v254, v219
	v_cvt_pk_fp8_f32 v253, v179, v254 op_sel:[0,0,1]
	ds_read_b128 v[122:125], v185 offset:0
	ds_read_b128 v[126:129], v186 offset:0
	ds_read_b128 v[114:117], v185 offset:2048
	ds_read_b128 v[118:121], v186 offset:2048
	ds_read_b128 v[106:109], v185 offset:4096
	ds_read_b128 v[110:113], v186 offset:4096
	ds_read_b128 v[98:101], v185 offset:6144
	ds_read_b128 v[102:105], v186 offset:6144
	s_waitcnt lgkmcnt(8)
	v_mfma_scale_f32_32x32x64_f8f6f4 v[66:81], v[222:229], v[130:137], v[66:81], v194, v193 op_sel_hi:[0,0,0]
	v_mov_b32_e32 v0, v219
	s_nop 1
	v_permlane32_swap_b32_e32 v219, v0
	v_add_f32_e32 v219, v219, v0
	v_fma_f32 v209, v209, v221, v219
	v_max_f32_e32 v177, v82, v83
	v_max3_f32 v177, v177, v84, v85
	v_max3_f32 v177, v177, v86, v87
	v_max3_f32 v177, v177, v88, v89
	v_max3_f32 v177, v177, v90, v91
	v_max3_f32 v177, v177, v92, v93
	v_max3_f32 v177, v177, v94, v95
	v_max3_f32 v177, v177, v96, v97
	s_waitcnt lgkmcnt(6)
	v_mfma_scale_f32_32x32x64_f8f6f4 v[50:65], v[246:253], v[122:129], v[50:65], v194, v194 op_sel_hi:[0,0,0]
	s_waitcnt lgkmcnt(4)
	v_mfma_scale_f32_32x32x64_f8f6f4 v[34:49], v[246:253], v[114:121], v[34:49], v194, v194 op_sel_hi:[0,0,0]
	s_waitcnt lgkmcnt(2)
	v_mfma_scale_f32_32x32x64_f8f6f4 v[18:33], v[246:253], v[106:113], v[18:33], v194, v194 op_sel_hi:[0,0,0]
	s_waitcnt vmcnt(0)
	ds_write_b128 v210, v[158:161] offset:43008
	ds_write_b128 v211, v[162:165] offset:51200
	ds_write_b128 v212, v[154:157] offset:59392
	s_waitcnt lgkmcnt(3)
	v_mfma_scale_f32_32x32x64_f8f6f4 v[2:17], v[246:253], v[98:105], v[2:17], v194, v194 op_sel_hi:[0,0,0]
	s_waitcnt lgkmcnt(0)
	s_barrier
	v_max_f32_e32 v0, v66, v67
	v_max3_f32 v0, v0, v68, v69
	v_max3_f32 v0, v0, v70, v71
	v_max3_f32 v0, v0, v72, v73
	v_max3_f32 v0, v0, v74, v75
	v_max3_f32 v0, v0, v76, v77
	v_max3_f32 v0, v0, v78, v79
	v_max3_f32 v0, v0, v80, v81
	v_max_f32_e32 v177, v177, v0
	v_mov_b32_e32 v0, v177
	v_mov_b32_e32 v218, 1.0
	s_nop 0
	v_permlane32_swap_b32_e32 v177, v0
	v_max_f32_e32 v177, v177, v0
	v_cmp_ge_f32_e32 vcc, s90, v177
	s_cmp_eq_u64 vcc, exec
	s_cbranch_scc0 .Lmla_h3_newmax
; __device__ __forceinline__ void finishSM9(f32x16& p0, f32x16& p1, float alpha, float& l_reg, v8i32& p8) {
; #pragma unroll
;   for (int r = 0; r < 16; ++r) { p0[r] = __builtin_amdgcn_exp2f(p0[r]); p1[r] = __builtin_amdgcn_exp2f(p1[r]); }
;   float ps = 0;
; #pragma unroll
;   for (int r = 0; r < 16; ++r) ps += p0[r];
; #pragma unroll
;   for (int r = 0; r < 16; ++r) ps += p1[r];
;   { auto rr = __builtin_amdgcn_permlane32_swap(__float_as_uint(ps), __float_as_uint(ps), false, false);
;     ps = __uint_as_float(rr[0]) + __uint_as_float(rr[1]); }
;   l_reg = l_reg * alpha + ps;
; #pragma unroll
;   for (int g = 0; g < 4; ++g) {
;     int w = __builtin_amdgcn_cvt_pk_fp8_f32(p0[4 * g], p0[4 * g + 1], 0, false); p8[g] = __builtin_amdgcn_cvt_pk_fp8_f32(p0[4 * g + 2], p0[4 * g + 3], w, true);
;     int u = __builtin_amdgcn_cvt_pk_fp8_f32(p1[4 * g], p1[4 * g + 1], 0, false); p8[4 + g] = __builtin_amdgcn_cvt_pk_fp8_f32(p1[4 * g + 2], p1[4 * g + 3], u, true); }
; }
; __device__ __forceinline__ void pv8(f32x16* o, const char* Vt, const v8i32 p8, int r32, int hi) {
;   const int sw = (r32 >> 2) & 3, a0 = r32 * 64 + (((hi * 2) ^ sw) << 4), a1 = r32 * 64 + (((hi * 2 + 1) ^ sw) << 4);
; #pragma unroll
;   for (int d0 = 0; d0 < 4; ++d0) {
;     const v8i32 vf = cat8(*reinterpret_cast<const v4i32*>(Vt + d0 * 2048 + a0), *reinterpret_cast<const v4i32*>(Vt + d0 * 2048 + a1));
;     o[d0] = __builtin_amdgcn_mfma_scale_f32_32x32x64_f8f6f4(p8, vf, o[d0], 0, 0, 0, 127, 0, 127); }
; }
; __device__ __forceinline__ void qkt9(f32x16& p0, f32x16& p1, const char* Kn, const char* Kr, const v8i32* qf, const float init, int r32, int hi) {
; #pragma unroll
;   for (int r = 0; r < 16; ++r) { p0[r] = init; p1[r] = init; }
; #pragma unroll
;   for (int s = 0; s < 2; ++s) { const int c0 = s * 4 + hi * 2;
;     const v8i32 a0 = cat8(*reinterpret_cast<const v4i32*>(Kn + KN8SW(r32, c0)), *reinterpret_cast<const v4i32*>(Kn + KN8SW(r32, c0 + 1)));
;     const v8i32 a1 = cat8(*reinterpret_cast<const v4i32*>(Kn + 4096 + KN8SW(r32, c0)), *reinterpret_cast<const v4i32*>(Kn + 4096 + KN8SW(r32, c0 + 1)));
;     p0 = __builtin_amdgcn_mfma_scale_f32_32x32x64_f8f6f4(a0, qf[s], p0, 0, 0, 0, 127, 0, 124);
;     p1 = __builtin_amdgcn_mfma_scale_f32_32x32x64_f8f6f4(a1, qf[s], p1, 0, 0, 0, 127, 0, 124); }
;   { const int c0 = hi * 2;
.Lmla_h3_cont:
	global_load_dwordx4 v[158:161], v176, s[18:19]
	global_load_dwordx4 v[162:165], v178, s[16:17]
	global_load_dwordx4 v[154:157], v[180:181], off
	ds_read_b128 v[114:117], v215 offset:51200
	ds_read_b128 v[118:121], v216 offset:51200
	ds_read_b128 v[222:225], v215 offset:55296
	ds_read_b128 v[226:229], v216 offset:55296
	v_add_u32_e32 v176, 0x2000, v176
	v_add_u32_e32 v178, 0x20000, v178
	s_mov_b64 s[20:21], 0x1000
	v_lshl_add_u64 v[180:181], v[180:181], 0, s[20:21]
	v_exp_f32_e32 v0, v82
	v_exp_f32_e32 v177, v83
	v_exp_f32_e32 v179, v84
	v_exp_f32_e32 v254, v85
	v_add_f32_e32 v219, v0, v177
	v_cvt_pk_fp8_f32 v246, v0, v177
	v_add_f32_e32 v219, v179, v219
	v_add_f32_e32 v219, v254, v219
	v_cvt_pk_fp8_f32 v246, v179, v254 op_sel:[0,0,1]
	s_waitcnt lgkmcnt(2)
	v_mfma_scale_f32_32x32x64_f8f6f4 v[114:129], v[114:121], v[146:153], v[230:245], v194, v193 op_sel_hi:[0,0,0]
	v_exp_f32_e32 v0, v86
	v_exp_f32_e32 v177, v87
	v_exp_f32_e32 v179, v88
	v_exp_f32_e32 v254, v89
	v_add_f32_e32 v219, v0, v219
	v_add_f32_e32 v219, v177, v219
	v_cvt_pk_fp8_f32 v247, v0, v177
	v_add_f32_e32 v219, v179, v219
	v_add_f32_e32 v219, v254, v219
	v_cvt_pk_fp8_f32 v247, v179, v254 op_sel:[0,0,1]
	ds_read_b128 v[82:85], v213 offset:51200
	ds_read_b128 v[86:89], v214 offset:51200
	s_waitcnt lgkmcnt(2)
	v_mfma_scale_f32_32x32x64_f8f6f4 v[98:113], v[222:229], v[146:153], v[230:245], v194, v193 op_sel_hi:[0,0,0]
	ds_read_b128 v[222:225], v213 offset:55296
	ds_read_b128 v[226:229], v214 offset:55296
	v_exp_f32_e32 v0, v90
	v_exp_f32_e32 v177, v91
	v_exp_f32_e32 v179, v92
	v_exp_f32_e32 v254, v93
	v_add_f32_e32 v219, v0, v219
	v_add_f32_e32 v219, v177, v219
	v_cvt_pk_fp8_f32 v248, v0, v177
	v_add_f32_e32 v219, v179, v219
	v_add_f32_e32 v219, v254, v219
	v_cvt_pk_fp8_f32 v248, v179, v254 op_sel:[0,0,1]
	v_exp_f32_e32 v0, v94
	v_exp_f32_e32 v177, v95
	v_exp_f32_e32 v179, v96
	v_exp_f32_e32 v254, v97
	v_add_f32_e32 v219, v0, v219
	v_add_f32_e32 v219, v177, v219
	v_cvt_pk_fp8_f32 v249, v0, v177
	v_add_f32_e32 v219, v179, v219
	v_add_f32_e32 v219, v254, v219
	v_cvt_pk_fp8_f32 v249, v179, v254 op_sel:[0,0,1]
	ds_read_b128 v[90:93], v185 offset:59392
	ds_read_b128 v[94:97], v186 offset:59392
	s_waitcnt lgkmcnt(4)
	v_mfma_scale_f32_32x32x64_f8f6f4 v[114:129], v[82:89], v[138:145], v[114:129], v194, v193 op_sel_hi:[0,0,0]
	v_exp_f32_e32 v0, v66
	v_exp_f32_e32 v177, v67
	v_exp_f32_e32 v179, v68
	v_exp_f32_e32 v254, v69
	v_add_f32_e32 v219, v0, v219
	v_add_f32_e32 v219, v177, v219
	v_cvt_pk_fp8_f32 v250, v0, v177
	v_add_f32_e32 v219, v179, v219
	v_add_f32_e32 v219, v254, v219
	v_cvt_pk_fp8_f32 v250, v179, v254 op_sel:[0,0,1]
	s_waitcnt lgkmcnt(2)
	v_mfma_scale_f32_32x32x64_f8f6f4 v[98:113], v[222:229], v[138:145], v[98:113], v194, v193 op_sel_hi:[0,0,0]
	ds_read_b128 v[222:225], v185 offset:61440
	ds_read_b128 v[226:229], v186 offset:61440
	v_exp_f32_e32 v0, v70
	v_exp_f32_e32 v177, v71
	v_exp_f32_e32 v179, v72
	v_exp_f32_e32 v254, v73
	v_add_f32_e32 v219, v0, v219
	v_add_f32_e32 v219, v177, v219
	v_cvt_pk_fp8_f32 v251, v0, v177
	v_add_f32_e32 v219, v179, v219
	v_add_f32_e32 v219, v254, v219
	v_cvt_pk_fp8_f32 v251, v179, v254 op_sel:[0,0,1]
	v_exp_f32_e32 v0, v74
	v_exp_f32_e32 v177, v75
	v_exp_f32_e32 v179, v76
	v_exp_f32_e32 v254, v77
	v_add_f32_e32 v219, v0, v219
	v_add_f32_e32 v219, v177, v219
	v_cvt_pk_fp8_f32 v252, v0, v177
	v_add_f32_e32 v219, v179, v219
	v_add_f32_e32 v219, v254, v219
	v_cvt_pk_fp8_f32 v252, v179, v254 op_sel:[0,0,1]
	s_waitcnt lgkmcnt(2)
	v_mfma_scale_f32_32x32x64_f8f6f4 v[114:129], v[90:97], v[130:137], v[114:129], v194, v193 op_sel_hi:[0,0,0]
	v_exp_f32_e32 v0, v78
	v_exp_f32_e32 v177, v79
	v_exp_f32_e32 v179, v80
	v_exp_f32_e32 v254, v81
	v_add_f32_e32 v219, v0, v219
	v_add_f32_e32 v219, v177, v219
	v_cvt_pk_fp8_f32 v253, v0, v177
	v_add_f32_e32 v219, v179, v219
	v_add_f32_e32 v219, v254, v219
	v_cvt_pk_fp8_f32 v253, v179, v254 op_sel:[0,0,1]
	ds_read_b128 v[90:93], v185 offset:8192
	ds_read_b128 v[94:97], v186 offset:8192
	ds_read_b128 v[82:85], v185 offset:10240
	ds_read_b128 v[86:89], v186 offset:10240
	ds_read_b128 v[74:77], v185 offset:12288
	ds_read_b128 v[78:81], v186 offset:12288
	ds_read_b128 v[66:69], v185 offset:14336
	ds_read_b128 v[70:73], v186 offset:14336
	s_waitcnt lgkmcnt(8)
	v_mfma_scale_f32_32x32x64_f8f6f4 v[98:113], v[222:229], v[130:137], v[98:113], v194, v193 op_sel_hi:[0,0,0]
	v_mov_b32_e32 v0, v219
	s_nop 1
	v_permlane32_swap_b32_e32 v219, v0
	v_add_f32_e32 v219, v219, v0
	v_fma_f32 v209, v209, v218, v219
	v_max_f32_e32 v177, v114, v115
	v_max3_f32 v177, v177, v116, v117
	v_max3_f32 v177, v177, v118, v119
	v_max3_f32 v177, v177, v120, v121
	v_max3_f32 v177, v177, v122, v123
	v_max3_f32 v177, v177, v124, v125
	v_max3_f32 v177, v177, v126, v127
	v_max3_f32 v177, v177, v128, v129
	s_waitcnt lgkmcnt(6)
	v_mfma_scale_f32_32x32x64_f8f6f4 v[50:65], v[246:253], v[90:97], v[50:65], v194, v194 op_sel_hi:[0,0,0]
	s_waitcnt lgkmcnt(4)
	v_mfma_scale_f32_32x32x64_f8f6f4 v[34:49], v[246:253], v[82:89], v[34:49], v194, v194 op_sel_hi:[0,0,0]
	s_waitcnt lgkmcnt(2)
	v_mfma_scale_f32_32x32x64_f8f6f4 v[18:33], v[246:253], v[74:81], v[18:33], v194, v194 op_sel_hi:[0,0,0]
	s_waitcnt vmcnt(0)
	ds_write_b128 v210, v[158:161]
	ds_write_b128 v211, v[162:165] offset:16384
	ds_write_b128 v212, v[154:157] offset:32768
	s_waitcnt lgkmcnt(3)
	v_mfma_scale_f32_32x32x64_f8f6f4 v[2:17], v[246:253], v[66:73], v[2:17], v194, v194 op_sel_hi:[0,0,0]
	s_waitcnt lgkmcnt(0)
	s_barrier
	v_max_f32_e32 v0, v98, v99
	v_max3_f32 v0, v0, v100, v101
	v_max3_f32 v0, v0, v102, v103
	v_max3_f32 v0, v0, v104, v105
	v_max3_f32 v0, v0, v106, v107
	v_max3_f32 v0, v0, v108, v109
	v_max3_f32 v0, v0, v110, v111
	v_max3_f32 v0, v0, v112, v113
	v_max_f32_e32 v177, v177, v0
	v_mov_b32_e32 v0, v177
	v_mov_b32_e32 v221, 1.0
	s_nop 0
	v_permlane32_swap_b32_e32 v177, v0
	v_max_f32_e32 v177, v177, v0
	v_cmp_ge_f32_e32 vcc, s90, v177
	s_cmp_eq_u64 vcc, exec
	s_cbranch_scc0 .Lmla_h4_newmax
; __device__ __forceinline__ void finishSM9(f32x16& p0, f32x16& p1, float alpha, float& l_reg, v8i32& p8) {
; #pragma unroll
;   for (int r = 0; r < 16; ++r) { p0[r] = __builtin_amdgcn_exp2f(p0[r]); p1[r] = __builtin_amdgcn_exp2f(p1[r]); }
;   float ps = 0;
; #pragma unroll
;   for (int r = 0; r < 16; ++r) ps += p0[r];
; #pragma unroll
;   for (int r = 0; r < 16; ++r) ps += p1[r];
;   { auto rr = __builtin_amdgcn_permlane32_swap(__float_as_uint(ps), __float_as_uint(ps), false, false);
;     ps = __uint_as_float(rr[0]) + __uint_as_float(rr[1]); }
;   l_reg = l_reg * alpha + ps;
; #pragma unroll
;   for (int g = 0; g < 4; ++g) {
;     int w = __builtin_amdgcn_cvt_pk_fp8_f32(p0[4 * g], p0[4 * g + 1], 0, false); p8[g] = __builtin_amdgcn_cvt_pk_fp8_f32(p0[4 * g + 2], p0[4 * g + 3], w, true);
;     int u = __builtin_amdgcn_cvt_pk_fp8_f32(p1[4 * g], p1[4 * g + 1], 0, false); p8[4 + g] = __builtin_amdgcn_cvt_pk_fp8_f32(p1[4 * g + 2], p1[4 * g + 3], u, true); }
; }
; __device__ __forceinline__ void pv8(f32x16* o, const char* Vt, const v8i32 p8, int r32, int hi) {
;   const int sw = (r32 >> 2) & 3, a0 = r32 * 64 + (((hi * 2) ^ sw) << 4), a1 = r32 * 64 + (((hi * 2 + 1) ^ sw) << 4);
; #pragma unroll
;   for (int d0 = 0; d0 < 4; ++d0) {
;     const v8i32 vf = cat8(*reinterpret_cast<const v4i32*>(Vt + d0 * 2048 + a0), *reinterpret_cast<const v4i32*>(Vt + d0 * 2048 + a1));
;     o[d0] = __builtin_amdgcn_mfma_scale_f32_32x32x64_f8f6f4(p8, vf, o[d0], 0, 0, 0, 127, 0, 127); }
; }
; __device__ __forceinline__ void qkt9(f32x16& p0, f32x16& p1, const char* Kn, const char* Kr, const v8i32* qf, const float init, int r32, int hi) {
; #pragma unroll
;   for (int r = 0; r < 16; ++r) { p0[r] = init; p1[r] = init; }
; #pragma unroll
;   for (int s = 0; s < 2; ++s) { const int c0 = s * 4 + hi * 2;
;     const v8i32 a0 = cat8(*reinterpret_cast<const v4i32*>(Kn + KN8SW(r32, c0)), *reinterpret_cast<const v4i32*>(Kn + KN8SW(r32, c0 + 1)));
;     const v8i32 a1 = cat8(*reinterpret_cast<const v4i32*>(Kn + 4096 + KN8SW(r32, c0)), *reinterpret_cast<const v4i32*>(Kn + 4096 + KN8SW(r32, c0 + 1)));
;     p0 = __builtin_amdgcn_mfma_scale_f32_32x32x64_f8f6f4(a0, qf[s], p0, 0, 0, 0, 127, 0, 124);
;     p1 = __builtin_amdgcn_mfma_scale_f32_32x32x64_f8f6f4(a1, qf[s], p1, 0, 0, 0, 127, 0, 124); }
;   { const int c0 = hi * 2;
.Lmla_h4_cont:
	global_load_dwordx4 v[158:161], v176, s[18:19]
	global_load_dwordx4 v[162:165], v178, s[16:17]
	global_load_dwordx4 v[154:157], v[180:181], off
	ds_read_b128 v[82:85], v215 offset:16384
	ds_read_b128 v[86:89], v216 offset:16384
	ds_read_b128 v[222:225], v215 offset:20480
	ds_read_b128 v[226:229], v216 offset:20480
	v_add_u32_e32 v176, 0x2000, v176
	v_add_u32_e32 v178, 0x20000, v178
	s_mov_b64 s[20:21], 0x1000
	v_lshl_add_u64 v[180:181], v[180:181], 0, s[20:21]
	v_exp_f32_e32 v0, v114
	v_exp_f32_e32 v177, v115
	v_exp_f32_e32 v179, v116
	v_exp_f32_e32 v254, v117
	v_add_f32_e32 v219, v0, v177
	v_cvt_pk_fp8_f32 v246, v0, v177
	v_add_f32_e32 v219, v179, v219
	v_add_f32_e32 v219, v254, v219
	v_cvt_pk_fp8_f32 v246, v179, v254 op_sel:[0,0,1]
	s_waitcnt lgkmcnt(2)
	v_mfma_scale_f32_32x32x64_f8f6f4 v[82:97], v[82:89], v[146:153], v[230:245], v194, v193 op_sel_hi:[0,0,0]
	v_exp_f32_e32 v0, v118
	v_exp_f32_e32 v177, v119
	v_exp_f32_e32 v179, v120
	v_exp_f32_e32 v254, v121
	v_add_f32_e32 v219, v0, v219
	v_add_f32_e32 v219, v177, v219
	v_cvt_pk_fp8_f32 v247, v0, v177
	v_add_f32_e32 v219, v179, v219
	v_add_f32_e32 v219, v254, v219
	v_cvt_pk_fp8_f32 v247, v179, v254 op_sel:[0,0,1]
	ds_read_b128 v[114:117], v213 offset:16384
	ds_read_b128 v[118:121], v214 offset:16384
	s_waitcnt lgkmcnt(2)
	v_mfma_scale_f32_32x32x64_f8f6f4 v[66:81], v[222:229], v[146:153], v[230:245], v194, v193 op_sel_hi:[0,0,0]
	ds_read_b128 v[222:225], v213 offset:20480
	ds_read_b128 v[226:229], v214 offset:20480
	v_exp_f32_e32 v0, v122
	v_exp_f32_e32 v177, v123
	v_exp_f32_e32 v179, v124
	v_exp_f32_e32 v254, v125
	v_add_f32_e32 v219, v0, v219
	v_add_f32_e32 v219, v177, v219
	v_cvt_pk_fp8_f32 v248, v0, v177
	v_add_f32_e32 v219, v179, v219
	v_add_f32_e32 v219, v254, v219
	v_cvt_pk_fp8_f32 v248, v179, v254 op_sel:[0,0,1]
	v_exp_f32_e32 v0, v126
	v_exp_f32_e32 v177, v127
	v_exp_f32_e32 v179, v128
	v_exp_f32_e32 v254, v129
	v_add_f32_e32 v219, v0, v219
	v_add_f32_e32 v219, v177, v219
	v_cvt_pk_fp8_f32 v249, v0, v177
	v_add_f32_e32 v219, v179, v219
	v_add_f32_e32 v219, v254, v219
	v_cvt_pk_fp8_f32 v249, v179, v254 op_sel:[0,0,1]
	ds_read_b128 v[122:125], v185 offset:32768
	ds_read_b128 v[126:129], v186 offset:32768
	s_waitcnt lgkmcnt(4)
	v_mfma_scale_f32_32x32x64_f8f6f4 v[82:97], v[114:121], v[138:145], v[82:97], v194, v193 op_sel_hi:[0,0,0]
	v_exp_f32_e32 v0, v98
	v_exp_f32_e32 v177, v99
	v_exp_f32_e32 v179, v100
	v_exp_f32_e32 v254, v101
	v_add_f32_e32 v219, v0, v219
	v_add_f32_e32 v219, v177, v219
	v_cvt_pk_fp8_f32 v250, v0, v177
	v_add_f32_e32 v219, v179, v219
	v_add_f32_e32 v219, v254, v219
	v_cvt_pk_fp8_f32 v250, v179, v254 op_sel:[0,0,1]
	s_waitcnt lgkmcnt(2)
	v_mfma_scale_f32_32x32x64_f8f6f4 v[66:81], v[222:229], v[138:145], v[66:81], v194, v193 op_sel_hi:[0,0,0]
	ds_read_b128 v[222:225], v185 offset:34816
	ds_read_b128 v[226:229], v186 offset:34816
	v_exp_f32_e32 v0, v102
	v_exp_f32_e32 v177, v103
	v_exp_f32_e32 v179, v104
	v_exp_f32_e32 v254, v105
	v_add_f32_e32 v219, v0, v219
	v_add_f32_e32 v219, v177, v219
	v_cvt_pk_fp8_f32 v251, v0, v177
	v_add_f32_e32 v219, v179, v219
	v_add_f32_e32 v219, v254, v219
	v_cvt_pk_fp8_f32 v251, v179, v254 op_sel:[0,0,1]
	v_exp_f32_e32 v0, v106
	v_exp_f32_e32 v177, v107
	v_exp_f32_e32 v179, v108
	v_exp_f32_e32 v254, v109
	v_add_f32_e32 v219, v0, v219
	v_add_f32_e32 v219, v177, v219
	v_cvt_pk_fp8_f32 v252, v0, v177
	v_add_f32_e32 v219, v179, v219
	v_add_f32_e32 v219, v254, v219
	v_cvt_pk_fp8_f32 v252, v179, v254 op_sel:[0,0,1]
	s_waitcnt lgkmcnt(2)
	v_mfma_scale_f32_32x32x64_f8f6f4 v[82:97], v[122:129], v[130:137], v[82:97], v194, v193 op_sel_hi:[0,0,0]
	v_exp_f32_e32 v0, v110
	v_exp_f32_e32 v177, v111
	v_exp_f32_e32 v179, v112
	v_exp_f32_e32 v254, v113
	v_add_f32_e32 v219, v0, v219
	v_add_f32_e32 v219, v177, v219
	v_cvt_pk_fp8_f32 v253, v0, v177
	v_add_f32_e32 v219, v179, v219
	v_add_f32_e32 v219, v254, v219
	v_cvt_pk_fp8_f32 v253, v179, v254 op_sel:[0,0,1]
	ds_read_b128 v[122:125], v185 offset:43008
	ds_read_b128 v[126:129], v186 offset:43008
	ds_read_b128 v[114:117], v185 offset:45056
	ds_read_b128 v[118:121], v186 offset:45056
	ds_read_b128 v[106:109], v185 offset:47104
	ds_read_b128 v[110:113], v186 offset:47104
	ds_read_b128 v[98:101], v185 offset:49152
	ds_read_b128 v[102:105], v186 offset:49152
	s_waitcnt lgkmcnt(8)
	v_mfma_scale_f32_32x32x64_f8f6f4 v[66:81], v[222:229], v[130:137], v[66:81], v194, v193 op_sel_hi:[0,0,0]
	v_mov_b32_e32 v0, v219
	s_nop 1
	v_permlane32_swap_b32_e32 v219, v0
	v_add_f32_e32 v219, v219, v0
	v_fma_f32 v209, v209, v221, v219
	v_max_f32_e32 v177, v82, v83
	v_max3_f32 v177, v177, v84, v85
	v_max3_f32 v177, v177, v86, v87
	v_max3_f32 v177, v177, v88, v89
	v_max3_f32 v177, v177, v90, v91
	v_max3_f32 v177, v177, v92, v93
	v_max3_f32 v177, v177, v94, v95
	v_max3_f32 v177, v177, v96, v97
	s_waitcnt lgkmcnt(6)
	v_mfma_scale_f32_32x32x64_f8f6f4 v[50:65], v[246:253], v[122:129], v[50:65], v194, v194 op_sel_hi:[0,0,0]
	s_waitcnt lgkmcnt(4)
	v_mfma_scale_f32_32x32x64_f8f6f4 v[34:49], v[246:253], v[114:121], v[34:49], v194, v194 op_sel_hi:[0,0,0]
	s_waitcnt lgkmcnt(2)
	v_mfma_scale_f32_32x32x64_f8f6f4 v[18:33], v[246:253], v[106:113], v[18:33], v194, v194 op_sel_hi:[0,0,0]
	s_waitcnt vmcnt(0)
	ds_write_b128 v210, v[158:161] offset:8192
	ds_write_b128 v211, v[162:165] offset:24576
	ds_write_b128 v212, v[154:157] offset:36864
	s_waitcnt lgkmcnt(3)
	v_mfma_scale_f32_32x32x64_f8f6f4 v[2:17], v[246:253], v[98:105], v[2:17], v194, v194 op_sel_hi:[0,0,0]
	s_waitcnt lgkmcnt(0)
	s_barrier
	v_max_f32_e32 v0, v66, v67
	v_max3_f32 v0, v0, v68, v69
	v_max3_f32 v0, v0, v70, v71
	v_max3_f32 v0, v0, v72, v73
	v_max3_f32 v0, v0, v74, v75
	v_max3_f32 v0, v0, v76, v77
	v_max3_f32 v0, v0, v78, v79
	v_max3_f32 v0, v0, v80, v81
	v_max_f32_e32 v177, v177, v0
	v_mov_b32_e32 v0, v177
	v_mov_b32_e32 v218, 1.0
	s_nop 0
	v_permlane32_swap_b32_e32 v177, v0
	v_max_f32_e32 v177, v177, v0
	v_cmp_ge_f32_e32 vcc, s90, v177
	s_cmp_eq_u64 vcc, exec
	s_cbranch_scc0 .Lmla_h5_newmax
; __device__ __forceinline__ void finishSM9(f32x16& p0, f32x16& p1, float alpha, float& l_reg, v8i32& p8) {
; #pragma unroll
;   for (int r = 0; r < 16; ++r) { p0[r] = __builtin_amdgcn_exp2f(p0[r]); p1[r] = __builtin_amdgcn_exp2f(p1[r]); }
;   float ps = 0;
; #pragma unroll
;   for (int r = 0; r < 16; ++r) ps += p0[r];
; #pragma unroll
;   for (int r = 0; r < 16; ++r) ps += p1[r];
;   { auto rr = __builtin_amdgcn_permlane32_swap(__float_as_uint(ps), __float_as_uint(ps), false, false);
;     ps = __uint_as_float(rr[0]) + __uint_as_float(rr[1]); }
;   l_reg = l_reg * alpha + ps;
; #pragma unroll
;   for (int g = 0; g < 4; ++g) {
;     int w = __builtin_amdgcn_cvt_pk_fp8_f32(p0[4 * g], p0[4 * g + 1], 0, false); p8[g] = __builtin_amdgcn_cvt_pk_fp8_f32(p0[4 * g + 2], p0[4 * g + 3], w, true);
;     int u = __builtin_amdgcn_cvt_pk_fp8_f32(p1[4 * g], p1[4 * g + 1], 0, false); p8[4 + g] = __builtin_amdgcn_cvt_pk_fp8_f32(p1[4 * g + 2], p1[4 * g + 3], u, true); }
; }
; __device__ __forceinline__ void pv8(f32x16* o, const char* Vt, const v8i32 p8, int r32, int hi) {
;   const int sw = (r32 >> 2) & 3, a0 = r32 * 64 + (((hi * 2) ^ sw) << 4), a1 = r32 * 64 + (((hi * 2 + 1) ^ sw) << 4);
; #pragma unroll
;   for (int d0 = 0; d0 < 4; ++d0) {
;     const v8i32 vf = cat8(*reinterpret_cast<const v4i32*>(Vt + d0 * 2048 + a0), *reinterpret_cast<const v4i32*>(Vt + d0 * 2048 + a1));
;     o[d0] = __builtin_amdgcn_mfma_scale_f32_32x32x64_f8f6f4(p8, vf, o[d0], 0, 0, 0, 127, 0, 127); }
; }
; __device__ __forceinline__ void qkt9(f32x16& p0, f32x16& p1, const char* Kn, const char* Kr, const v8i32* qf, const float init, int r32, int hi) {
; #pragma unroll
;   for (int r = 0; r < 16; ++r) { p0[r] = init; p1[r] = init; }
; #pragma unroll
;   for (int s = 0; s < 2; ++s) { const int c0 = s * 4 + hi * 2;
;     const v8i32 a0 = cat8(*reinterpret_cast<const v4i32*>(Kn + KN8SW(r32, c0)), *reinterpret_cast<const v4i32*>(Kn + KN8SW(r32, c0 + 1)));
;     const v8i32 a1 = cat8(*reinterpret_cast<const v4i32*>(Kn + 4096 + KN8SW(r32, c0)), *reinterpret_cast<const v4i32*>(Kn + 4096 + KN8SW(r32, c0 + 1)));
;     p0 = __builtin_amdgcn_mfma_scale_f32_32x32x64_f8f6f4(a0, qf[s], p0, 0, 0, 0, 127, 0, 124);
;     p1 = __builtin_amdgcn_mfma_scale_f32_32x32x64_f8f6f4(a1, qf[s], p1, 0, 0, 0, 127, 0, 124); }
;   { const int c0 = hi * 2;
.Lmla_h5_cont:
	s_add_i32 s30, s30, 1
	s_cmpk_lt_u32 s30, 42
	s_cbranch_scc1 .LBB0_1321
	global_load_dwordx4 v[158:161], v176, s[18:19]
	global_load_dwordx4 v[162:165], v178, s[16:17]
	global_load_dwordx4 v[154:157], v[180:181], off
	ds_read_b128 v[114:117], v215 offset:24576
	ds_read_b128 v[118:121], v216 offset:24576
	ds_read_b128 v[222:225], v215 offset:28672
	ds_read_b128 v[226:229], v216 offset:28672
	v_add_u32_e32 v176, 0x2000, v176
	v_add_u32_e32 v178, 0x20000, v178
	s_mov_b64 s[20:21], 0x1000
	v_lshl_add_u64 v[180:181], v[180:181], 0, s[20:21]
	v_exp_f32_e32 v0, v82
	v_exp_f32_e32 v177, v83
	v_exp_f32_e32 v179, v84
	v_exp_f32_e32 v254, v85
	v_add_f32_e32 v219, v0, v177
	v_cvt_pk_fp8_f32 v246, v0, v177
	v_add_f32_e32 v219, v179, v219
	v_add_f32_e32 v219, v254, v219
	v_cvt_pk_fp8_f32 v246, v179, v254 op_sel:[0,0,1]
	s_waitcnt lgkmcnt(2)
	v_mfma_scale_f32_32x32x64_f8f6f4 v[114:129], v[114:121], v[146:153], v[230:245], v194, v193 op_sel_hi:[0,0,0]
	v_exp_f32_e32 v0, v86
	v_exp_f32_e32 v177, v87
	v_exp_f32_e32 v179, v88
	v_exp_f32_e32 v254, v89
	v_add_f32_e32 v219, v0, v219
	v_add_f32_e32 v219, v177, v219
	v_cvt_pk_fp8_f32 v247, v0, v177
	v_add_f32_e32 v219, v179, v219
	v_add_f32_e32 v219, v254, v219
	v_cvt_pk_fp8_f32 v247, v179, v254 op_sel:[0,0,1]
	ds_read_b128 v[82:85], v213 offset:24576
	ds_read_b128 v[86:89], v214 offset:24576
	s_waitcnt lgkmcnt(2)
	v_mfma_scale_f32_32x32x64_f8f6f4 v[98:113], v[222:229], v[146:153], v[230:245], v194, v193 op_sel_hi:[0,0,0]
	ds_read_b128 v[222:225], v213 offset:28672
	ds_read_b128 v[226:229], v214 offset:28672
	v_exp_f32_e32 v0, v90
	v_exp_f32_e32 v177, v91
	v_exp_f32_e32 v179, v92
	v_exp_f32_e32 v254, v93
	v_add_f32_e32 v219, v0, v219
	v_add_f32_e32 v219, v177, v219
	v_cvt_pk_fp8_f32 v248, v0, v177
	v_add_f32_e32 v219, v179, v219
	v_add_f32_e32 v219, v254, v219
	v_cvt_pk_fp8_f32 v248, v179, v254 op_sel:[0,0,1]
	v_exp_f32_e32 v0, v94
	v_exp_f32_e32 v177, v95
	v_exp_f32_e32 v179, v96
	v_exp_f32_e32 v254, v97
	v_add_f32_e32 v219, v0, v219
	v_add_f32_e32 v219, v177, v219
	v_cvt_pk_fp8_f32 v249, v0, v177
	v_add_f32_e32 v219, v179, v219
	v_add_f32_e32 v219, v254, v219
	v_cvt_pk_fp8_f32 v249, v179, v254 op_sel:[0,0,1]
	ds_read_b128 v[90:93], v185 offset:36864
	ds_read_b128 v[94:97], v186 offset:36864
	s_waitcnt lgkmcnt(4)
	v_mfma_scale_f32_32x32x64_f8f6f4 v[114:129], v[82:89], v[138:145], v[114:129], v194, v193 op_sel_hi:[0,0,0]
	v_exp_f32_e32 v0, v66
	v_exp_f32_e32 v177, v67
	v_exp_f32_e32 v179, v68
	v_exp_f32_e32 v254, v69
	v_add_f32_e32 v219, v0, v219
	v_add_f32_e32 v219, v177, v219
	v_cvt_pk_fp8_f32 v250, v0, v177
	v_add_f32_e32 v219, v179, v219
	v_add_f32_e32 v219, v254, v219
	v_cvt_pk_fp8_f32 v250, v179, v254 op_sel:[0,0,1]
	s_waitcnt lgkmcnt(2)
	v_mfma_scale_f32_32x32x64_f8f6f4 v[98:113], v[222:229], v[138:145], v[98:113], v194, v193 op_sel_hi:[0,0,0]
	ds_read_b128 v[222:225], v185 offset:38912
	ds_read_b128 v[226:229], v186 offset:38912
	v_exp_f32_e32 v0, v70
	v_exp_f32_e32 v177, v71
	v_exp_f32_e32 v179, v72
	v_exp_f32_e32 v254, v73
	v_add_f32_e32 v219, v0, v219
	v_add_f32_e32 v219, v177, v219
	v_cvt_pk_fp8_f32 v251, v0, v177
	v_add_f32_e32 v219, v179, v219
	v_add_f32_e32 v219, v254, v219
	v_cvt_pk_fp8_f32 v251, v179, v254 op_sel:[0,0,1]
	v_exp_f32_e32 v0, v74
	v_exp_f32_e32 v177, v75
	v_exp_f32_e32 v179, v76
	v_exp_f32_e32 v254, v77
	v_add_f32_e32 v219, v0, v219
	v_add_f32_e32 v219, v177, v219
	v_cvt_pk_fp8_f32 v252, v0, v177
	v_add_f32_e32 v219, v179, v219
	v_add_f32_e32 v219, v254, v219
	v_cvt_pk_fp8_f32 v252, v179, v254 op_sel:[0,0,1]
	s_waitcnt lgkmcnt(2)
	v_mfma_scale_f32_32x32x64_f8f6f4 v[114:129], v[90:97], v[130:137], v[114:129], v194, v193 op_sel_hi:[0,0,0]
	v_exp_f32_e32 v0, v78
	v_exp_f32_e32 v177, v79
	v_exp_f32_e32 v179, v80
	v_exp_f32_e32 v254, v81
	v_add_f32_e32 v219, v0, v219
	v_add_f32_e32 v219, v177, v219
	v_cvt_pk_fp8_f32 v253, v0, v177
	v_add_f32_e32 v219, v179, v219
	v_add_f32_e32 v219, v254, v219
	v_cvt_pk_fp8_f32 v253, v179, v254 op_sel:[0,0,1]
	ds_read_b128 v[90:93], v185 offset:0
	ds_read_b128 v[94:97], v186 offset:0
	ds_read_b128 v[82:85], v185 offset:2048
	ds_read_b128 v[86:89], v186 offset:2048
	ds_read_b128 v[74:77], v185 offset:4096
	ds_read_b128 v[78:81], v186 offset:4096
	ds_read_b128 v[66:69], v185 offset:6144
	ds_read_b128 v[70:73], v186 offset:6144
	s_waitcnt lgkmcnt(8)
	v_mfma_scale_f32_32x32x64_f8f6f4 v[98:113], v[222:229], v[130:137], v[98:113], v194, v193 op_sel_hi:[0,0,0]
	v_mov_b32_e32 v0, v219
	s_nop 1
	v_permlane32_swap_b32_e32 v219, v0
	v_add_f32_e32 v219, v219, v0
	v_fma_f32 v209, v209, v218, v219
	v_max_f32_e32 v177, v114, v115
	v_max3_f32 v177, v177, v116, v117
	v_max3_f32 v177, v177, v118, v119
	v_max3_f32 v177, v177, v120, v121
	v_max3_f32 v177, v177, v122, v123
	v_max3_f32 v177, v177, v124, v125
	v_max3_f32 v177, v177, v126, v127
	v_max3_f32 v177, v177, v128, v129
	s_waitcnt lgkmcnt(6)
	v_mfma_scale_f32_32x32x64_f8f6f4 v[50:65], v[246:253], v[90:97], v[50:65], v194, v194 op_sel_hi:[0,0,0]
	s_waitcnt lgkmcnt(4)
	v_mfma_scale_f32_32x32x64_f8f6f4 v[34:49], v[246:253], v[82:89], v[34:49], v194, v194 op_sel_hi:[0,0,0]
	s_waitcnt lgkmcnt(2)
	v_mfma_scale_f32_32x32x64_f8f6f4 v[18:33], v[246:253], v[74:81], v[18:33], v194, v194 op_sel_hi:[0,0,0]
	s_waitcnt vmcnt(0)
	ds_write_b128 v210, v[158:161] offset:43008
	ds_write_b128 v211, v[162:165] offset:51200
	ds_write_b128 v212, v[154:157] offset:59392
	s_waitcnt lgkmcnt(3)
	v_mfma_scale_f32_32x32x64_f8f6f4 v[2:17], v[246:253], v[66:73], v[2:17], v194, v194 op_sel_hi:[0,0,0]
	s_waitcnt lgkmcnt(0)
	s_barrier
	v_max_f32_e32 v0, v98, v99
	v_max3_f32 v0, v0, v100, v101
	v_max3_f32 v0, v0, v102, v103
	v_max3_f32 v0, v0, v104, v105
	v_max3_f32 v0, v0, v106, v107
	v_max3_f32 v0, v0, v108, v109
	v_max3_f32 v0, v0, v110, v111
	v_max3_f32 v0, v0, v112, v113
	v_max_f32_e32 v177, v177, v0
	v_mov_b32_e32 v0, v177
	v_mov_b32_e32 v221, 1.0
	s_nop 0
	v_permlane32_swap_b32_e32 v177, v0
	v_max_f32_e32 v177, v177, v0
	v_cmp_ge_f32_e32 vcc, s90, v177
	s_cmp_eq_u64 vcc, exec
	s_cbranch_scc0 .Lmla_p0_newmax

; #define RESC(a) do { if (__any((a) < 1.f)) { if (hi == 0) al_l[r32] = (a); asm volatile("s_waitcnt lgkmcnt(0)" ::: "memory"); \
;     _Pragma("unroll") for (int d = 0; d < 4; ++d) _Pragma("unroll") for (int r = 0; r < 16; ++r) o[d][r] *= al_l[crow(r, hi)]; } } while (0)
; #define RESC(a) do { if (__any((a) < 1.f)) { if (hi == 0) al_l[r32] = (a); asm volatile("s_waitcnt lgkmcnt(0)" ::: "memory"); \
;     _Pragma("unroll") for (int d = 0; d < 4; ++d) _Pragma("unroll") for (int r = 0; r < 16; ++r) o[d][r] *= al_l[crow(r, hi)]; } } while (0)
; #define RESC(a) do { if (__any((a) < 1.f)) { if (hi == 0) al_l[r32] = (a); asm volatile("s_waitcnt lgkmcnt(0)" ::: "memory"); \
;     _Pragma("unroll") for (int d = 0; d < 4; ++d) _Pragma("unroll") for (int r = 0; r < 16; ++r) o[d][r] *= al_l[crow(r, hi)]; } } while (0)
; __device__ __forceinline__ void attn_unit7(const unsigned char* __restrict__ Q8, int ldq, const unsigned char* __restrict__ Kn8, int ldk, const unsigned char* __restrict__ Kr8, ...
;     ...
;   qkt9(pB0, pB1, Kn_lds + 8192, Kr_lds + 4096, qf, 7.0f - m_reg, r32, hi);
;   finishSM9(pA0, pA1, alA, l_reg, p8);
;   pv8(o, Vt_lds, p8, r32, hi); partialSM9(pB0, pB1, m_reg, alB, thr_raw);
;   RESC(alB);
;   finishSM9(pB0, pB1, alB, l_reg, p8);
;   pv8(o, Vt_lds + 8192, p8, r32, hi);
.Lmla_p1_cont:
	v_mov_b32_e32 v0, v218
	s_branch .LBB0_1343
.Lmla_stag_entry:
	global_load_dwordx4 v[158:161], v176, s[18:19]
	global_load_dwordx4 v[162:165], v178, s[16:17]
	s_nop 1
	v_add_u32_e32 v176, 0x2000, v176
	v_add_u32_e32 v178, 0x20000, v178
